# prologue adaLN GEMV: weight-row loads kept three 8-row batches ahead (x4 unrolled register ring) instead of waiting for each batch
# speedup vs baseline: 1.0079x; 1.0079x over previous
; DI void phase_prologue(const Params& p, int bid, int nblk, char* smem) {
;     ...
;       float acc[17];
; #pragma unroll
;       for (int j = 0; j < 17; ++j) acc[j] = 0.f;
;       const float* wa = p.in[I_WADA] + (size_t)l * 1024 * 6144 + col0 + col;
;       for (int k0 = kq * 256; k0 < kq * 256 + 256; k0 += 8) {
;         float wv[8];
; #pragma unroll
;         for (int kk = 0; kk < 8; ++kk) wv[kk] = wa[(size_t)(k0 + kk) * 6144];
; #pragma unroll
;         for (int kk = 0; kk < 8; ++kk)
; #pragma unroll
;           for (int j = 0; j < 17; ++j) acc[j] += scs[j * 1024 + k0 + kk] * wv[kk];
;       }
.LBB0_22:
	s_or_b64 exec, exec, s[26:27]
	s_mul_hi_i32 s16, s53, 0x2aaaaaab
	s_lshr_b32 s17, s16, 31
	s_ashr_i32 s20, s16, 4
	s_add_i32 s20, s20, s17
	s_mul_i32 s16, s20, 0x60
	s_sub_i32 s16, s53, s16
	s_lshl_b32 s16, s16, 6
	s_ashr_i32 s17, s16, 31
	s_mul_i32 s26, s20, 0x1800000
	s_lshl_b64 s[18:19], s[16:17], 2
	s_mul_hi_i32 s21, s20, 0x1800000
	s_add_u32 s18, s26, s18
	s_addc_u32 s19, s21, s19
	v_mov_b32_e32 v182, 0
	v_lshl_add_u64 v[140:141], v[138:139], 0, s[18:19]
	s_mov_b64 s[18:19], 0
	v_mov_b32_e32 v180, v177
	v_mov_b32_e32 v181, v176
	v_mov_b32_e32 v146, 0
	v_mov_b32_e32 v147, v182
	v_mov_b32_e32 v142, 0
	v_mov_b32_e32 v143, v182
	v_mov_b32_e32 v144, 0
	v_mov_b32_e32 v145, v182
	v_mov_b32_e32 v148, 0
	v_mov_b32_e32 v149, v182
	v_mov_b32_e32 v150, 0
	v_mov_b32_e32 v151, v182
	v_mov_b32_e32 v152, 0
	v_mov_b32_e32 v153, v182
	v_mov_b32_e32 v154, 0
	v_mov_b32_e32 v155, v182
	v_mov_b32_e32 v156, 0
	v_mov_b32_e32 v157, v182
	s_mov_b32 s56, 0xffffa000
	s_mov_b32 s57, -1
	s_mov_b64 s[58:59], s[24:25]
	global_load_dword v192, v[140:141], off
	v_lshl_add_u64 v[226:227], v[140:141], 0, s[56:57]
	global_load_dword v199, v[226:227], off
	v_lshl_add_u64 v[228:229], v[226:227], 0, s[56:57]
	global_load_dword v198, v[228:229], off
	v_lshl_add_u64 v[230:231], v[228:229], 0, s[56:57]
	global_load_dword v197, v[230:231], off
	v_lshl_add_u64 v[232:233], v[230:231], 0, s[56:57]
	global_load_dword v196, v[232:233], off
	v_lshl_add_u64 v[234:235], v[232:233], 0, s[56:57]
	global_load_dword v195, v[234:235], off
	v_lshl_add_u64 v[236:237], v[234:235], 0, s[56:57]
	global_load_dword v194, v[236:237], off
	v_lshl_add_u64 v[238:239], v[236:237], 0, s[56:57]
	global_load_dword v193, v[238:239], off
	v_lshl_add_u64 v[240:241], v[140:141], 0, s[58:59]
	global_load_dword v200, v[240:241], off
	v_lshl_add_u64 v[226:227], v[240:241], 0, s[56:57]
	global_load_dword v207, v[226:227], off
	v_lshl_add_u64 v[228:229], v[226:227], 0, s[56:57]
	global_load_dword v206, v[228:229], off
	v_lshl_add_u64 v[230:231], v[228:229], 0, s[56:57]
	global_load_dword v205, v[230:231], off
	v_lshl_add_u64 v[232:233], v[230:231], 0, s[56:57]
	global_load_dword v204, v[232:233], off
	v_lshl_add_u64 v[234:235], v[232:233], 0, s[56:57]
	global_load_dword v203, v[234:235], off
	v_lshl_add_u64 v[236:237], v[234:235], 0, s[56:57]
	global_load_dword v202, v[236:237], off
	v_lshl_add_u64 v[238:239], v[236:237], 0, s[56:57]
	global_load_dword v201, v[238:239], off
	v_lshl_add_u64 v[240:241], v[240:241], 0, s[58:59]
	global_load_dword v208, v[240:241], off
	v_lshl_add_u64 v[226:227], v[240:241], 0, s[56:57]
	global_load_dword v215, v[226:227], off
	v_lshl_add_u64 v[228:229], v[226:227], 0, s[56:57]
	global_load_dword v214, v[228:229], off
	v_lshl_add_u64 v[230:231], v[228:229], 0, s[56:57]
	global_load_dword v213, v[230:231], off
	v_lshl_add_u64 v[232:233], v[230:231], 0, s[56:57]
	global_load_dword v212, v[232:233], off
	v_lshl_add_u64 v[234:235], v[232:233], 0, s[56:57]
	global_load_dword v211, v[234:235], off
	v_lshl_add_u64 v[236:237], v[234:235], 0, s[56:57]
	global_load_dword v210, v[236:237], off
	v_lshl_add_u64 v[238:239], v[236:237], 0, s[56:57]
	global_load_dword v209, v[238:239], off
	s_waitcnt lgkmcnt(0)
	s_barrier
.LBB0_23:
	s_waitcnt vmcnt(16)
	v_mov_b32_e32 v134, v192
	v_mov_b32_e32 v186, v193
	v_mov_b32_e32 v188, v194
	v_mov_b32_e32 v189, v195
	v_mov_b32_e32 v162, v196
	v_mov_b32_e32 v163, v197
	v_mov_b32_e32 v164, v198
	v_mov_b32_e32 v165, v199
	s_nop 0
	ds_read_b128 v[22:25], v180
	ds_read_b128 v[18:21], v180 offset:16
	ds_read_b128 v[6:9], v180 offset:4096
	ds_read_b128 v[2:5], v180 offset:4112
	ds_read_b128 v[34:37], v180 offset:8192
	ds_read_b128 v[42:45], v180 offset:8208
	ds_read_b128 v[14:17], v180 offset:12288
	ds_read_b128 v[10:13], v180 offset:12304
	ds_read_b128 v[46:49], v180 offset:16384
	ds_read_b128 v[58:61], v180 offset:16400
	ds_read_b128 v[30:33], v180 offset:20480
	ds_read_b128 v[26:29], v180 offset:20496
	ds_read_b128 v[66:69], v180 offset:24576
	ds_read_b128 v[74:77], v180 offset:24592
	ds_read_b128 v[50:53], v180 offset:28672
	ds_read_b128 v[38:41], v180 offset:28688
	ds_read_b128 v[78:81], v180 offset:32768
	ds_read_b128 v[86:89], v180 offset:32784
	ds_read_b128 v[62:65], v180 offset:36864
	ds_read_b128 v[54:57], v180 offset:36880
	ds_read_b128 v[94:97], v180 offset:40960
	ds_read_b128 v[102:105], v180 offset:40976
	ds_read_b128 v[82:85], v180 offset:45056
	ds_read_b128 v[70:73], v180 offset:45072
	ds_read_b128 v[110:113], v180 offset:49152
	ds_read_b128 v[114:117], v180 offset:49168
	ds_read_b128 v[98:101], v180 offset:53248
	ds_read_b128 v[90:93], v180 offset:53264
	ds_read_b128 v[122:125], v180 offset:57344
	ds_read_b128 v[126:129], v180 offset:57360
	ds_read_b128 v[118:121], v180 offset:61440
	ds_read_b128 v[106:109], v180 offset:61456
	v_add_u32_e32 v183, 0x10000, v180
	s_nop 0
	v_add_u32_e32 v184, 0x1000c, v180
	s_nop 0
	v_add_u32_e32 v185, 0x10014, v180
	s_nop 0
	v_add_u32_e32 v187, 0x1001c, v180
	s_nop 0
	v_add_u32_e32 v181, 8, v181
	v_add_u32_e32 v242, 16, v181
	v_mov_b32_e32 v216, 0x90000
	v_cmp_lt_i32_e32 vcc, v242, v133
	s_nop 1
	v_cndmask_b32_e32 v216, 0, v216, vcc
	v_mov_b32_e32 v217, 0
	v_lshl_add_u64 v[240:241], v[140:141], 0, v[216:217]
	global_load_dword v244, v[240:241], off
	v_lshl_add_u64 v[226:227], v[240:241], 0, s[56:57]
	global_load_dword v251, v[226:227], off
	v_lshl_add_u64 v[228:229], v[226:227], 0, s[56:57]
	global_load_dword v250, v[228:229], off
	v_lshl_add_u64 v[230:231], v[228:229], 0, s[56:57]
	global_load_dword v249, v[230:231], off
	v_lshl_add_u64 v[232:233], v[230:231], 0, s[56:57]
	global_load_dword v248, v[232:233], off
	v_lshl_add_u64 v[234:235], v[232:233], 0, s[56:57]
	global_load_dword v247, v[234:235], off
	v_lshl_add_u64 v[236:237], v[234:235], 0, s[56:57]
	global_load_dword v246, v[236:237], off
	v_lshl_add_u64 v[238:239], v[236:237], 0, s[56:57]
	global_load_dword v245, v[238:239], off
	s_nop 0
	s_nop 0
	s_nop 0
	ds_read_b96 v[158:160], v183
	ds_read2_b32 v[166:167], v184 offset1:1
	ds_read2_b32 v[168:169], v185 offset1:1
	ds_read_b32 v183, v187
	s_waitcnt lgkmcnt(14)
; DI void phase_prologue(const Params& p, int bid, int nblk, char* smem) {
;     ...
;       for (int k0 = kq * 256; k0 < kq * 256 + 256; k0 += 8) {
;         float wv[8];
; #pragma unroll
;         for (int kk = 0; kk < 8; ++kk) wv[kk] = wa[(size_t)(k0 + kk) * 6144];
; #pragma unroll
;         for (int kk = 0; kk < 8; ++kk)
; #pragma unroll
;           for (int j = 0; j < 17; ++j) acc[j] += scs[j * 1024 + k0 + kk] * wv[kk];
;       }
	v_mov_b32_e32 v170, v22
	v_mov_b32_e32 v171, v6
	v_mov_b32_e32 v6, v23
	v_mov_b32_e32 v22, v24
	v_mov_b32_e32 v23, v8
	v_mov_b32_e32 v8, v25
	v_mov_b32_e32 v24, v18
	v_mov_b32_e32 v25, v2
	v_mov_b32_e32 v2, v19
	v_mov_b32_e32 v18, v20
	v_mov_b32_e32 v19, v4
	v_mov_b32_e32 v4, v21
	v_mov_b32_e32 v20, v34
	v_mov_b32_e32 v21, v14
	v_mov_b32_e32 v14, v35
	v_mov_b32_e32 v34, v36
	v_mov_b32_e32 v35, v16
	v_mov_b32_e32 v16, v37
	v_mov_b32_e32 v36, v42
	v_mov_b32_e32 v37, v10
	v_mov_b32_e32 v10, v43
	v_mov_b32_e32 v42, v44
	v_mov_b32_e32 v43, v12
	v_mov_b32_e32 v12, v45
	v_mov_b32_e32 v44, v46
	v_mov_b32_e32 v45, v30
	v_mov_b32_e32 v30, v47
	v_mov_b32_e32 v46, v48
	v_mov_b32_e32 v47, v32
	v_mov_b32_e32 v32, v49
	v_mov_b32_e32 v48, v58
	v_mov_b32_e32 v49, v26
	v_mov_b32_e32 v26, v59
	v_mov_b32_e32 v58, v60
	v_mov_b32_e32 v59, v28
	v_mov_b32_e32 v28, v61
	v_mov_b32_e32 v60, v66
	v_mov_b32_e32 v61, v50
	v_mov_b32_e32 v50, v67
	v_mov_b32_e32 v66, v68
	v_mov_b32_e32 v67, v52
	v_mov_b32_e32 v52, v69
	v_mov_b32_e32 v68, v74
	v_mov_b32_e32 v69, v38
	v_mov_b32_e32 v38, v75
	v_mov_b32_e32 v74, v76
	v_mov_b32_e32 v75, v40
	v_mov_b32_e32 v40, v77
	v_mov_b32_e32 v76, v78
	v_mov_b32_e32 v77, v62
	v_mov_b32_e32 v62, v79
	v_mov_b32_e32 v78, v80
	v_mov_b32_e32 v79, v64
	v_mov_b32_e32 v64, v81
	v_mov_b32_e32 v80, v86
	v_mov_b32_e32 v81, v54
	v_mov_b32_e32 v54, v87
	v_mov_b32_e32 v86, v88
	v_mov_b32_e32 v87, v56
	v_mov_b32_e32 v56, v89
	v_mov_b32_e32 v88, v94
	s_waitcnt lgkmcnt(13)
	v_mov_b32_e32 v89, v82
	v_mov_b32_e32 v82, v95
	v_mov_b32_e32 v94, v96
	v_mov_b32_e32 v95, v84
	v_mov_b32_e32 v84, v97
	v_mov_b32_e32 v96, v102
	s_waitcnt lgkmcnt(12)
	v_mov_b32_e32 v97, v70
	v_mov_b32_e32 v70, v103
	v_mov_b32_e32 v102, v104
	v_mov_b32_e32 v103, v72
	v_mov_b32_e32 v72, v105
	s_waitcnt lgkmcnt(11)
	v_mov_b32_e32 v104, v110
	s_waitcnt lgkmcnt(9)
	v_mov_b32_e32 v105, v98
	v_mov_b32_e32 v98, v111
	v_mov_b32_e32 v110, v112
	v_mov_b32_e32 v111, v100
	v_mov_b32_e32 v100, v113
	v_mov_b32_e32 v112, v114
	s_waitcnt lgkmcnt(8)
	v_mov_b32_e32 v113, v90
	v_mov_b32_e32 v90, v115
	v_mov_b32_e32 v114, v116
	v_mov_b32_e32 v115, v92
	v_mov_b32_e32 v92, v117
	s_waitcnt lgkmcnt(7)
	v_mov_b32_e32 v116, v122
	s_waitcnt lgkmcnt(5)
	v_mov_b32_e32 v117, v118
	v_mov_b32_e32 v118, v123
	v_mov_b32_e32 v122, v124
	v_mov_b32_e32 v123, v120
	v_mov_b32_e32 v120, v125
	v_mov_b32_e32 v124, v126
	s_waitcnt lgkmcnt(4)
	v_mov_b32_e32 v125, v106
	v_mov_b32_e32 v106, v127
	v_mov_b32_e32 v126, v128
	v_mov_b32_e32 v127, v108
	v_mov_b32_e32 v108, v129
	s_waitcnt lgkmcnt(3)
	v_mov_b32_e32 v128, v159
	v_mov_b32_e32 v129, v160
	v_fmac_f32_e32 v182, v186, v158
	v_pk_mul_f32 v[128:129], v[188:189], v[128:129]
	v_pk_fma_f32 v[146:147], v[186:187], v[170:171], v[146:147] op_sel_hi:[0,1,1]
	v_pk_fma_f32 v[20:21], v[186:187], v[20:21], v[142:143] op_sel_hi:[0,1,1]
	v_pk_fma_f32 v[44:45], v[186:187], v[44:45], v[144:145] op_sel_hi:[0,1,1]
	v_pk_fma_f32 v[60:61], v[186:187], v[60:61], v[148:149] op_sel_hi:[0,1,1]
	v_pk_fma_f32 v[76:77], v[186:187], v[76:77], v[150:151] op_sel_hi:[0,1,1]
	v_pk_fma_f32 v[88:89], v[186:187], v[88:89], v[152:153] op_sel_hi:[0,1,1]
	v_pk_fma_f32 v[104:105], v[186:187], v[104:105], v[154:155] op_sel_hi:[0,1,1]
	v_pk_fma_f32 v[116:117], v[186:187], v[116:117], v[156:157] op_sel_hi:[0,1,1]
	s_waitcnt lgkmcnt(2)
	v_pk_mul_f32 v[158:159], v[162:163], v[166:167]
	v_mov_b32_e32 v166, v189
	v_add_f32_e32 v128, v182, v128
	v_pk_fma_f32 v[6:7], v[188:189], v[6:7], v[146:147] op_sel_hi:[0,1,1]
	v_pk_fma_f32 v[14:15], v[188:189], v[14:15], v[20:21] op_sel_hi:[0,1,1]
	v_pk_fma_f32 v[20:21], v[188:189], v[30:31], v[44:45] op_sel_hi:[0,1,1]
	v_pk_fma_f32 v[30:31], v[188:189], v[50:51], v[60:61] op_sel_hi:[0,1,1]
	v_pk_fma_f32 v[44:45], v[188:189], v[62:63], v[76:77] op_sel_hi:[0,1,1]
	v_pk_fma_f32 v[50:51], v[188:189], v[82:83], v[88:89] op_sel_hi:[0,1,1]
	v_pk_fma_f32 v[60:61], v[188:189], v[98:99], v[104:105] op_sel_hi:[0,1,1]
	v_pk_fma_f32 v[62:63], v[188:189], v[118:119], v[116:117] op_sel_hi:[0,1,1]
	v_add_f32_e32 v76, v128, v129
	v_pk_fma_f32 v[6:7], v[166:167], v[22:23], v[6:7] op_sel_hi:[0,1,1]
	v_pk_fma_f32 v[14:15], v[166:167], v[34:35], v[14:15] op_sel_hi:[0,1,1]
	v_pk_fma_f32 v[20:21], v[166:167], v[46:47], v[20:21] op_sel_hi:[0,1,1]
	v_pk_fma_f32 v[22:23], v[166:167], v[66:67], v[30:31] op_sel_hi:[0,1,1]
	v_pk_fma_f32 v[30:31], v[166:167], v[78:79], v[44:45] op_sel_hi:[0,1,1]
	v_pk_fma_f32 v[34:35], v[166:167], v[94:95], v[50:51] op_sel_hi:[0,1,1]
	v_pk_fma_f32 v[44:45], v[166:167], v[110:111], v[60:61] op_sel_hi:[0,1,1]
	v_pk_fma_f32 v[46:47], v[166:167], v[122:123], v[62:63] op_sel_hi:[0,1,1]
	s_waitcnt lgkmcnt(1)
; DI void phase_prologue(const Params& p, int bid, int nblk, char* smem) {
;     ...
;       for (int k0 = kq * 256; k0 < kq * 256 + 256; k0 += 8) {
;         float wv[8];
; #pragma unroll
;         for (int kk = 0; kk < 8; ++kk) wv[kk] = wa[(size_t)(k0 + kk) * 6144];
; #pragma unroll
;         for (int kk = 0; kk < 8; ++kk)
; #pragma unroll
;           for (int j = 0; j < 17; ++j) acc[j] += scs[j * 1024 + k0 + kk] * wv[kk];
;       }
	v_pk_mul_f32 v[160:161], v[164:165], v[168:169]
	v_mov_b32_e32 v168, v163
	v_add_f32_e32 v50, v76, v158
	v_pk_fma_f32 v[6:7], v[162:163], v[8:9], v[6:7] op_sel_hi:[0,1,1]
	v_pk_fma_f32 v[8:9], v[162:163], v[16:17], v[14:15] op_sel_hi:[0,1,1]
	v_pk_fma_f32 v[14:15], v[162:163], v[32:33], v[20:21] op_sel_hi:[0,1,1]
	v_pk_fma_f32 v[16:17], v[162:163], v[52:53], v[22:23] op_sel_hi:[0,1,1]
	v_pk_fma_f32 v[20:21], v[162:163], v[64:65], v[30:31] op_sel_hi:[0,1,1]
	v_pk_fma_f32 v[22:23], v[162:163], v[84:85], v[34:35] op_sel_hi:[0,1,1]
	v_pk_fma_f32 v[30:31], v[162:163], v[100:101], v[44:45] op_sel_hi:[0,1,1]
	v_pk_fma_f32 v[32:33], v[162:163], v[120:121], v[46:47] op_sel_hi:[0,1,1]
	v_add_f32_e32 v34, v50, v159
	v_pk_fma_f32 v[6:7], v[168:169], v[24:25], v[6:7] op_sel_hi:[0,1,1]
	v_pk_fma_f32 v[8:9], v[168:169], v[36:37], v[8:9] op_sel_hi:[0,1,1]
	v_pk_fma_f32 v[14:15], v[168:169], v[48:49], v[14:15] op_sel_hi:[0,1,1]
	v_pk_fma_f32 v[16:17], v[168:169], v[68:69], v[16:17] op_sel_hi:[0,1,1]
	v_pk_fma_f32 v[20:21], v[168:169], v[80:81], v[20:21] op_sel_hi:[0,1,1]
	v_pk_fma_f32 v[22:23], v[168:169], v[96:97], v[22:23] op_sel_hi:[0,1,1]
	v_pk_fma_f32 v[24:25], v[168:169], v[112:113], v[30:31] op_sel_hi:[0,1,1]
	v_pk_fma_f32 v[30:31], v[168:169], v[124:125], v[32:33] op_sel_hi:[0,1,1]
	v_mov_b32_e32 v170, v165
	v_add_f32_e32 v32, v34, v160
	v_pk_fma_f32 v[2:3], v[164:165], v[2:3], v[6:7] op_sel_hi:[0,1,1]
	v_pk_fma_f32 v[6:7], v[164:165], v[10:11], v[8:9] op_sel_hi:[0,1,1]
	v_pk_fma_f32 v[8:9], v[164:165], v[26:27], v[14:15] op_sel_hi:[0,1,1]
	v_pk_fma_f32 v[10:11], v[164:165], v[38:39], v[16:17] op_sel_hi:[0,1,1]
	v_pk_fma_f32 v[14:15], v[164:165], v[54:55], v[20:21] op_sel_hi:[0,1,1]
	v_pk_fma_f32 v[16:17], v[164:165], v[70:71], v[22:23] op_sel_hi:[0,1,1]
	v_pk_fma_f32 v[20:21], v[164:165], v[90:91], v[24:25] op_sel_hi:[0,1,1]
	v_pk_fma_f32 v[22:23], v[164:165], v[106:107], v[30:31] op_sel_hi:[0,1,1]
	v_cmp_ge_i32_e32 vcc, v181, v133
	v_add_f32_e32 v182, v32, v161
	v_pk_fma_f32 v[2:3], v[170:171], v[18:19], v[2:3] op_sel_hi:[0,1,1]
	v_pk_fma_f32 v[6:7], v[170:171], v[42:43], v[6:7] op_sel_hi:[0,1,1]
	v_pk_fma_f32 v[8:9], v[170:171], v[58:59], v[8:9] op_sel_hi:[0,1,1]
	v_pk_fma_f32 v[10:11], v[170:171], v[74:75], v[10:11] op_sel_hi:[0,1,1]
	v_pk_fma_f32 v[14:15], v[170:171], v[86:87], v[14:15] op_sel_hi:[0,1,1]
	v_pk_fma_f32 v[16:17], v[170:171], v[102:103], v[16:17] op_sel_hi:[0,1,1]
	v_pk_fma_f32 v[18:19], v[170:171], v[114:115], v[20:21] op_sel_hi:[0,1,1]
	v_pk_fma_f32 v[20:21], v[170:171], v[126:127], v[22:23] op_sel_hi:[0,1,1]
	v_add_u32_e32 v180, 32, v180
	v_lshl_add_u64 v[140:141], v[140:141], 0, s[24:25]
	s_or_b64 s[18:19], vcc, s[18:19]
	v_pk_fma_f32 v[146:147], v[134:135], v[4:5], v[2:3] op_sel_hi:[0,1,1]
	v_pk_fma_f32 v[142:143], v[134:135], v[12:13], v[6:7] op_sel_hi:[0,1,1]
	v_pk_fma_f32 v[144:145], v[134:135], v[28:29], v[8:9] op_sel_hi:[0,1,1]
	v_pk_fma_f32 v[148:149], v[134:135], v[40:41], v[10:11] op_sel_hi:[0,1,1]
	v_pk_fma_f32 v[150:151], v[134:135], v[56:57], v[14:15] op_sel_hi:[0,1,1]
	v_pk_fma_f32 v[152:153], v[134:135], v[72:73], v[16:17] op_sel_hi:[0,1,1]
	v_pk_fma_f32 v[154:155], v[134:135], v[92:93], v[18:19] op_sel_hi:[0,1,1]
	v_pk_fma_f32 v[156:157], v[134:135], v[108:109], v[20:21] op_sel_hi:[0,1,1]
	s_waitcnt lgkmcnt(0)
	v_fmac_f32_e32 v182, v134, v183
	s_waitcnt vmcnt(16)
	v_mov_b32_e32 v134, v200
	v_mov_b32_e32 v186, v201
	v_mov_b32_e32 v188, v202
	v_mov_b32_e32 v189, v203
	v_mov_b32_e32 v162, v204
	v_mov_b32_e32 v163, v205
	v_mov_b32_e32 v164, v206
	v_mov_b32_e32 v165, v207
	s_nop 0
	ds_read_b128 v[22:25], v180
	ds_read_b128 v[18:21], v180 offset:16
	ds_read_b128 v[6:9], v180 offset:4096
	ds_read_b128 v[2:5], v180 offset:4112
	ds_read_b128 v[34:37], v180 offset:8192
	ds_read_b128 v[42:45], v180 offset:8208
	ds_read_b128 v[14:17], v180 offset:12288
	ds_read_b128 v[10:13], v180 offset:12304
	ds_read_b128 v[46:49], v180 offset:16384
	ds_read_b128 v[58:61], v180 offset:16400
	ds_read_b128 v[30:33], v180 offset:20480
	ds_read_b128 v[26:29], v180 offset:20496
	ds_read_b128 v[66:69], v180 offset:24576
	ds_read_b128 v[74:77], v180 offset:24592
	ds_read_b128 v[50:53], v180 offset:28672
	ds_read_b128 v[38:41], v180 offset:28688
	ds_read_b128 v[78:81], v180 offset:32768
	ds_read_b128 v[86:89], v180 offset:32784
	ds_read_b128 v[62:65], v180 offset:36864
	ds_read_b128 v[54:57], v180 offset:36880
	ds_read_b128 v[94:97], v180 offset:40960
	ds_read_b128 v[102:105], v180 offset:40976
	ds_read_b128 v[82:85], v180 offset:45056
	ds_read_b128 v[70:73], v180 offset:45072
	ds_read_b128 v[110:113], v180 offset:49152
	ds_read_b128 v[114:117], v180 offset:49168
	ds_read_b128 v[98:101], v180 offset:53248
	ds_read_b128 v[90:93], v180 offset:53264
	ds_read_b128 v[122:125], v180 offset:57344
	ds_read_b128 v[126:129], v180 offset:57360
	ds_read_b128 v[118:121], v180 offset:61440
	ds_read_b128 v[106:109], v180 offset:61456
	v_add_u32_e32 v183, 0x10000, v180
	s_nop 0
	v_add_u32_e32 v184, 0x1000c, v180
	s_nop 0
	v_add_u32_e32 v185, 0x10014, v180
	s_nop 0
	v_add_u32_e32 v187, 0x1001c, v180
	s_nop 0
	v_add_u32_e32 v181, 8, v181
	v_add_u32_e32 v242, 16, v181
	v_mov_b32_e32 v216, 0x90000
	v_cmp_lt_i32_e32 vcc, v242, v133
	s_nop 1
	v_cndmask_b32_e32 v216, 0, v216, vcc
	v_mov_b32_e32 v217, 0
	v_lshl_add_u64 v[240:241], v[140:141], 0, v[216:217]
	global_load_dword v192, v[240:241], off
	v_lshl_add_u64 v[226:227], v[240:241], 0, s[56:57]
	global_load_dword v199, v[226:227], off
	v_lshl_add_u64 v[228:229], v[226:227], 0, s[56:57]
	global_load_dword v198, v[228:229], off
	v_lshl_add_u64 v[230:231], v[228:229], 0, s[56:57]
	global_load_dword v197, v[230:231], off
	v_lshl_add_u64 v[232:233], v[230:231], 0, s[56:57]
	global_load_dword v196, v[232:233], off
	v_lshl_add_u64 v[234:235], v[232:233], 0, s[56:57]
	global_load_dword v195, v[234:235], off
	v_lshl_add_u64 v[236:237], v[234:235], 0, s[56:57]
	global_load_dword v194, v[236:237], off
	v_lshl_add_u64 v[238:239], v[236:237], 0, s[56:57]
	global_load_dword v193, v[238:239], off
	s_nop 0
	s_nop 0
	s_nop 0
	ds_read_b96 v[158:160], v183
	ds_read2_b32 v[166:167], v184 offset1:1
	ds_read2_b32 v[168:169], v185 offset1:1
	ds_read_b32 v183, v187
	s_waitcnt lgkmcnt(14)
; DI void phase_prologue(const Params& p, int bid, int nblk, char* smem) {
;     ...
;       for (int k0 = kq * 256; k0 < kq * 256 + 256; k0 += 8) {
;         float wv[8];
; #pragma unroll
;         for (int kk = 0; kk < 8; ++kk) wv[kk] = wa[(size_t)(k0 + kk) * 6144];
; #pragma unroll
;         for (int kk = 0; kk < 8; ++kk)
; #pragma unroll
;           for (int j = 0; j < 17; ++j) acc[j] += scs[j * 1024 + k0 + kk] * wv[kk];
;       }
	v_mov_b32_e32 v170, v22
	v_mov_b32_e32 v171, v6
	v_mov_b32_e32 v6, v23
	v_mov_b32_e32 v22, v24
	v_mov_b32_e32 v23, v8
	v_mov_b32_e32 v8, v25
	v_mov_b32_e32 v24, v18
	v_mov_b32_e32 v25, v2
	v_mov_b32_e32 v2, v19
	v_mov_b32_e32 v18, v20
	v_mov_b32_e32 v19, v4
	v_mov_b32_e32 v4, v21
	v_mov_b32_e32 v20, v34
	v_mov_b32_e32 v21, v14
	v_mov_b32_e32 v14, v35
	v_mov_b32_e32 v34, v36
	v_mov_b32_e32 v35, v16
	v_mov_b32_e32 v16, v37
	v_mov_b32_e32 v36, v42
	v_mov_b32_e32 v37, v10
	v_mov_b32_e32 v10, v43
	v_mov_b32_e32 v42, v44
	v_mov_b32_e32 v43, v12
	v_mov_b32_e32 v12, v45
	v_mov_b32_e32 v44, v46
	v_mov_b32_e32 v45, v30
	v_mov_b32_e32 v30, v47
	v_mov_b32_e32 v46, v48
	v_mov_b32_e32 v47, v32
	v_mov_b32_e32 v32, v49
	v_mov_b32_e32 v48, v58
	v_mov_b32_e32 v49, v26
	v_mov_b32_e32 v26, v59
	v_mov_b32_e32 v58, v60
	v_mov_b32_e32 v59, v28
	v_mov_b32_e32 v28, v61
	v_mov_b32_e32 v60, v66
	v_mov_b32_e32 v61, v50
	v_mov_b32_e32 v50, v67
	v_mov_b32_e32 v66, v68
	v_mov_b32_e32 v67, v52
	v_mov_b32_e32 v52, v69
	v_mov_b32_e32 v68, v74
	v_mov_b32_e32 v69, v38
	v_mov_b32_e32 v38, v75
	v_mov_b32_e32 v74, v76
	v_mov_b32_e32 v75, v40
	v_mov_b32_e32 v40, v77
	v_mov_b32_e32 v76, v78
	v_mov_b32_e32 v77, v62
	v_mov_b32_e32 v62, v79
	v_mov_b32_e32 v78, v80
	v_mov_b32_e32 v79, v64
	v_mov_b32_e32 v64, v81
	v_mov_b32_e32 v80, v86
	v_mov_b32_e32 v81, v54
	v_mov_b32_e32 v54, v87
	v_mov_b32_e32 v86, v88
	v_mov_b32_e32 v87, v56
	v_mov_b32_e32 v56, v89
	v_mov_b32_e32 v88, v94
	s_waitcnt lgkmcnt(13)
	v_mov_b32_e32 v89, v82
	v_mov_b32_e32 v82, v95
	v_mov_b32_e32 v94, v96
	v_mov_b32_e32 v95, v84
	v_mov_b32_e32 v84, v97
	v_mov_b32_e32 v96, v102
	s_waitcnt lgkmcnt(12)
	v_mov_b32_e32 v97, v70
	v_mov_b32_e32 v70, v103
	v_mov_b32_e32 v102, v104
	v_mov_b32_e32 v103, v72
	v_mov_b32_e32 v72, v105
	s_waitcnt lgkmcnt(11)
	v_mov_b32_e32 v104, v110
	s_waitcnt lgkmcnt(9)
	v_mov_b32_e32 v105, v98
	v_mov_b32_e32 v98, v111
	v_mov_b32_e32 v110, v112
	v_mov_b32_e32 v111, v100
	v_mov_b32_e32 v100, v113
	v_mov_b32_e32 v112, v114
	s_waitcnt lgkmcnt(8)
	v_mov_b32_e32 v113, v90
	v_mov_b32_e32 v90, v115
	v_mov_b32_e32 v114, v116
	v_mov_b32_e32 v115, v92
	v_mov_b32_e32 v92, v117
	s_waitcnt lgkmcnt(7)
	v_mov_b32_e32 v116, v122
	s_waitcnt lgkmcnt(5)
	v_mov_b32_e32 v117, v118
	v_mov_b32_e32 v118, v123
	v_mov_b32_e32 v122, v124
	v_mov_b32_e32 v123, v120
	v_mov_b32_e32 v120, v125
	v_mov_b32_e32 v124, v126
	s_waitcnt lgkmcnt(4)
	v_mov_b32_e32 v125, v106
	v_mov_b32_e32 v106, v127
	v_mov_b32_e32 v126, v128
	v_mov_b32_e32 v127, v108
	v_mov_b32_e32 v108, v129
	s_waitcnt lgkmcnt(3)
	v_mov_b32_e32 v128, v159
	v_mov_b32_e32 v129, v160
	v_fmac_f32_e32 v182, v186, v158
	v_pk_mul_f32 v[128:129], v[188:189], v[128:129]
	v_pk_fma_f32 v[146:147], v[186:187], v[170:171], v[146:147] op_sel_hi:[0,1,1]
	v_pk_fma_f32 v[20:21], v[186:187], v[20:21], v[142:143] op_sel_hi:[0,1,1]
	v_pk_fma_f32 v[44:45], v[186:187], v[44:45], v[144:145] op_sel_hi:[0,1,1]
	v_pk_fma_f32 v[60:61], v[186:187], v[60:61], v[148:149] op_sel_hi:[0,1,1]
	v_pk_fma_f32 v[76:77], v[186:187], v[76:77], v[150:151] op_sel_hi:[0,1,1]
	v_pk_fma_f32 v[88:89], v[186:187], v[88:89], v[152:153] op_sel_hi:[0,1,1]
	v_pk_fma_f32 v[104:105], v[186:187], v[104:105], v[154:155] op_sel_hi:[0,1,1]
	v_pk_fma_f32 v[116:117], v[186:187], v[116:117], v[156:157] op_sel_hi:[0,1,1]
	s_waitcnt lgkmcnt(2)
	v_pk_mul_f32 v[158:159], v[162:163], v[166:167]
	v_mov_b32_e32 v166, v189
	v_add_f32_e32 v128, v182, v128
	v_pk_fma_f32 v[6:7], v[188:189], v[6:7], v[146:147] op_sel_hi:[0,1,1]
	v_pk_fma_f32 v[14:15], v[188:189], v[14:15], v[20:21] op_sel_hi:[0,1,1]
	v_pk_fma_f32 v[20:21], v[188:189], v[30:31], v[44:45] op_sel_hi:[0,1,1]
	v_pk_fma_f32 v[30:31], v[188:189], v[50:51], v[60:61] op_sel_hi:[0,1,1]
	v_pk_fma_f32 v[44:45], v[188:189], v[62:63], v[76:77] op_sel_hi:[0,1,1]
	v_pk_fma_f32 v[50:51], v[188:189], v[82:83], v[88:89] op_sel_hi:[0,1,1]
	v_pk_fma_f32 v[60:61], v[188:189], v[98:99], v[104:105] op_sel_hi:[0,1,1]
	v_pk_fma_f32 v[62:63], v[188:189], v[118:119], v[116:117] op_sel_hi:[0,1,1]
	v_add_f32_e32 v76, v128, v129
	v_pk_fma_f32 v[6:7], v[166:167], v[22:23], v[6:7] op_sel_hi:[0,1,1]
	v_pk_fma_f32 v[14:15], v[166:167], v[34:35], v[14:15] op_sel_hi:[0,1,1]
	v_pk_fma_f32 v[20:21], v[166:167], v[46:47], v[20:21] op_sel_hi:[0,1,1]
	v_pk_fma_f32 v[22:23], v[166:167], v[66:67], v[30:31] op_sel_hi:[0,1,1]
	v_pk_fma_f32 v[30:31], v[166:167], v[78:79], v[44:45] op_sel_hi:[0,1,1]
	v_pk_fma_f32 v[34:35], v[166:167], v[94:95], v[50:51] op_sel_hi:[0,1,1]
	v_pk_fma_f32 v[44:45], v[166:167], v[110:111], v[60:61] op_sel_hi:[0,1,1]
	v_pk_fma_f32 v[46:47], v[166:167], v[122:123], v[62:63] op_sel_hi:[0,1,1]
	s_waitcnt lgkmcnt(1)
; DI void phase_prologue(const Params& p, int bid, int nblk, char* smem) {
;     ...
;       for (int k0 = kq * 256; k0 < kq * 256 + 256; k0 += 8) {
;         float wv[8];
; #pragma unroll
;         for (int kk = 0; kk < 8; ++kk) wv[kk] = wa[(size_t)(k0 + kk) * 6144];
; #pragma unroll
;         for (int kk = 0; kk < 8; ++kk)
; #pragma unroll
;           for (int j = 0; j < 17; ++j) acc[j] += scs[j * 1024 + k0 + kk] * wv[kk];
;       }
	v_pk_mul_f32 v[160:161], v[164:165], v[168:169]
	v_mov_b32_e32 v168, v163
	v_add_f32_e32 v50, v76, v158
	v_pk_fma_f32 v[6:7], v[162:163], v[8:9], v[6:7] op_sel_hi:[0,1,1]
	v_pk_fma_f32 v[8:9], v[162:163], v[16:17], v[14:15] op_sel_hi:[0,1,1]
	v_pk_fma_f32 v[14:15], v[162:163], v[32:33], v[20:21] op_sel_hi:[0,1,1]
	v_pk_fma_f32 v[16:17], v[162:163], v[52:53], v[22:23] op_sel_hi:[0,1,1]
	v_pk_fma_f32 v[20:21], v[162:163], v[64:65], v[30:31] op_sel_hi:[0,1,1]
	v_pk_fma_f32 v[22:23], v[162:163], v[84:85], v[34:35] op_sel_hi:[0,1,1]
	v_pk_fma_f32 v[30:31], v[162:163], v[100:101], v[44:45] op_sel_hi:[0,1,1]
	v_pk_fma_f32 v[32:33], v[162:163], v[120:121], v[46:47] op_sel_hi:[0,1,1]
	v_add_f32_e32 v34, v50, v159
	v_pk_fma_f32 v[6:7], v[168:169], v[24:25], v[6:7] op_sel_hi:[0,1,1]
	v_pk_fma_f32 v[8:9], v[168:169], v[36:37], v[8:9] op_sel_hi:[0,1,1]
	v_pk_fma_f32 v[14:15], v[168:169], v[48:49], v[14:15] op_sel_hi:[0,1,1]
	v_pk_fma_f32 v[16:17], v[168:169], v[68:69], v[16:17] op_sel_hi:[0,1,1]
	v_pk_fma_f32 v[20:21], v[168:169], v[80:81], v[20:21] op_sel_hi:[0,1,1]
	v_pk_fma_f32 v[22:23], v[168:169], v[96:97], v[22:23] op_sel_hi:[0,1,1]
	v_pk_fma_f32 v[24:25], v[168:169], v[112:113], v[30:31] op_sel_hi:[0,1,1]
	v_pk_fma_f32 v[30:31], v[168:169], v[124:125], v[32:33] op_sel_hi:[0,1,1]
	v_mov_b32_e32 v170, v165
	v_add_f32_e32 v32, v34, v160
	v_pk_fma_f32 v[2:3], v[164:165], v[2:3], v[6:7] op_sel_hi:[0,1,1]
	v_pk_fma_f32 v[6:7], v[164:165], v[10:11], v[8:9] op_sel_hi:[0,1,1]
	v_pk_fma_f32 v[8:9], v[164:165], v[26:27], v[14:15] op_sel_hi:[0,1,1]
	v_pk_fma_f32 v[10:11], v[164:165], v[38:39], v[16:17] op_sel_hi:[0,1,1]
	v_pk_fma_f32 v[14:15], v[164:165], v[54:55], v[20:21] op_sel_hi:[0,1,1]
	v_pk_fma_f32 v[16:17], v[164:165], v[70:71], v[22:23] op_sel_hi:[0,1,1]
	v_pk_fma_f32 v[20:21], v[164:165], v[90:91], v[24:25] op_sel_hi:[0,1,1]
	v_pk_fma_f32 v[22:23], v[164:165], v[106:107], v[30:31] op_sel_hi:[0,1,1]
	v_cmp_ge_i32_e32 vcc, v181, v133
	v_add_f32_e32 v182, v32, v161
	v_pk_fma_f32 v[2:3], v[170:171], v[18:19], v[2:3] op_sel_hi:[0,1,1]
	v_pk_fma_f32 v[6:7], v[170:171], v[42:43], v[6:7] op_sel_hi:[0,1,1]
	v_pk_fma_f32 v[8:9], v[170:171], v[58:59], v[8:9] op_sel_hi:[0,1,1]
	v_pk_fma_f32 v[10:11], v[170:171], v[74:75], v[10:11] op_sel_hi:[0,1,1]
	v_pk_fma_f32 v[14:15], v[170:171], v[86:87], v[14:15] op_sel_hi:[0,1,1]
	v_pk_fma_f32 v[16:17], v[170:171], v[102:103], v[16:17] op_sel_hi:[0,1,1]
	v_pk_fma_f32 v[18:19], v[170:171], v[114:115], v[20:21] op_sel_hi:[0,1,1]
	v_pk_fma_f32 v[20:21], v[170:171], v[126:127], v[22:23] op_sel_hi:[0,1,1]
	v_add_u32_e32 v180, 32, v180
	v_lshl_add_u64 v[140:141], v[140:141], 0, s[24:25]
	s_or_b64 s[18:19], vcc, s[18:19]
	v_pk_fma_f32 v[146:147], v[134:135], v[4:5], v[2:3] op_sel_hi:[0,1,1]
	v_pk_fma_f32 v[142:143], v[134:135], v[12:13], v[6:7] op_sel_hi:[0,1,1]
	v_pk_fma_f32 v[144:145], v[134:135], v[28:29], v[8:9] op_sel_hi:[0,1,1]
	v_pk_fma_f32 v[148:149], v[134:135], v[40:41], v[10:11] op_sel_hi:[0,1,1]
	v_pk_fma_f32 v[150:151], v[134:135], v[56:57], v[14:15] op_sel_hi:[0,1,1]
	v_pk_fma_f32 v[152:153], v[134:135], v[72:73], v[16:17] op_sel_hi:[0,1,1]
	v_pk_fma_f32 v[154:155], v[134:135], v[92:93], v[18:19] op_sel_hi:[0,1,1]
	v_pk_fma_f32 v[156:157], v[134:135], v[108:109], v[20:21] op_sel_hi:[0,1,1]
	s_waitcnt lgkmcnt(0)
	v_fmac_f32_e32 v182, v134, v183
	s_waitcnt vmcnt(16)
	v_mov_b32_e32 v134, v208
	v_mov_b32_e32 v186, v209
	v_mov_b32_e32 v188, v210
	v_mov_b32_e32 v189, v211
	v_mov_b32_e32 v162, v212
	v_mov_b32_e32 v163, v213
	v_mov_b32_e32 v164, v214
	v_mov_b32_e32 v165, v215
	s_nop 0
	ds_read_b128 v[22:25], v180
	ds_read_b128 v[18:21], v180 offset:16
	ds_read_b128 v[6:9], v180 offset:4096
	ds_read_b128 v[2:5], v180 offset:4112
	ds_read_b128 v[34:37], v180 offset:8192
	ds_read_b128 v[42:45], v180 offset:8208
	ds_read_b128 v[14:17], v180 offset:12288
	ds_read_b128 v[10:13], v180 offset:12304
	ds_read_b128 v[46:49], v180 offset:16384
	ds_read_b128 v[58:61], v180 offset:16400
	ds_read_b128 v[30:33], v180 offset:20480
	ds_read_b128 v[26:29], v180 offset:20496
	ds_read_b128 v[66:69], v180 offset:24576
	ds_read_b128 v[74:77], v180 offset:24592
	ds_read_b128 v[50:53], v180 offset:28672
	ds_read_b128 v[38:41], v180 offset:28688
	ds_read_b128 v[78:81], v180 offset:32768
	ds_read_b128 v[86:89], v180 offset:32784
	ds_read_b128 v[62:65], v180 offset:36864
	ds_read_b128 v[54:57], v180 offset:36880
	ds_read_b128 v[94:97], v180 offset:40960
	ds_read_b128 v[102:105], v180 offset:40976
	ds_read_b128 v[82:85], v180 offset:45056
	ds_read_b128 v[70:73], v180 offset:45072
	ds_read_b128 v[110:113], v180 offset:49152
	ds_read_b128 v[114:117], v180 offset:49168
	ds_read_b128 v[98:101], v180 offset:53248
	ds_read_b128 v[90:93], v180 offset:53264
	ds_read_b128 v[122:125], v180 offset:57344
	ds_read_b128 v[126:129], v180 offset:57360
	ds_read_b128 v[118:121], v180 offset:61440
	ds_read_b128 v[106:109], v180 offset:61456
	v_add_u32_e32 v183, 0x10000, v180
	s_nop 0
	v_add_u32_e32 v184, 0x1000c, v180
	s_nop 0
	v_add_u32_e32 v185, 0x10014, v180
	s_nop 0
	v_add_u32_e32 v187, 0x1001c, v180
	s_nop 0
	v_add_u32_e32 v181, 8, v181
	v_add_u32_e32 v242, 16, v181
	v_mov_b32_e32 v216, 0x90000
	v_cmp_lt_i32_e32 vcc, v242, v133
	s_nop 1
	v_cndmask_b32_e32 v216, 0, v216, vcc
	v_mov_b32_e32 v217, 0
	v_lshl_add_u64 v[240:241], v[140:141], 0, v[216:217]
	global_load_dword v200, v[240:241], off
	v_lshl_add_u64 v[226:227], v[240:241], 0, s[56:57]
	global_load_dword v207, v[226:227], off
	v_lshl_add_u64 v[228:229], v[226:227], 0, s[56:57]
	global_load_dword v206, v[228:229], off
	v_lshl_add_u64 v[230:231], v[228:229], 0, s[56:57]
	global_load_dword v205, v[230:231], off
	v_lshl_add_u64 v[232:233], v[230:231], 0, s[56:57]
	global_load_dword v204, v[232:233], off
	v_lshl_add_u64 v[234:235], v[232:233], 0, s[56:57]
	global_load_dword v203, v[234:235], off
	v_lshl_add_u64 v[236:237], v[234:235], 0, s[56:57]
	global_load_dword v202, v[236:237], off
	v_lshl_add_u64 v[238:239], v[236:237], 0, s[56:57]
	global_load_dword v201, v[238:239], off
	s_nop 0
	s_nop 0
	s_nop 0
	ds_read_b96 v[158:160], v183
	ds_read2_b32 v[166:167], v184 offset1:1
	ds_read2_b32 v[168:169], v185 offset1:1
	ds_read_b32 v183, v187
	s_waitcnt lgkmcnt(14)
; DI void phase_prologue(const Params& p, int bid, int nblk, char* smem) {
;     ...
;       for (int k0 = kq * 256; k0 < kq * 256 + 256; k0 += 8) {
;         float wv[8];
; #pragma unroll
;         for (int kk = 0; kk < 8; ++kk) wv[kk] = wa[(size_t)(k0 + kk) * 6144];
; #pragma unroll
;         for (int kk = 0; kk < 8; ++kk)
; #pragma unroll
;           for (int j = 0; j < 17; ++j) acc[j] += scs[j * 1024 + k0 + kk] * wv[kk];
;       }
	v_mov_b32_e32 v170, v22
	v_mov_b32_e32 v171, v6
	v_mov_b32_e32 v6, v23
	v_mov_b32_e32 v22, v24
	v_mov_b32_e32 v23, v8
	v_mov_b32_e32 v8, v25
	v_mov_b32_e32 v24, v18
	v_mov_b32_e32 v25, v2
	v_mov_b32_e32 v2, v19
	v_mov_b32_e32 v18, v20
	v_mov_b32_e32 v19, v4
	v_mov_b32_e32 v4, v21
	v_mov_b32_e32 v20, v34
	v_mov_b32_e32 v21, v14
	v_mov_b32_e32 v14, v35
	v_mov_b32_e32 v34, v36
	v_mov_b32_e32 v35, v16
	v_mov_b32_e32 v16, v37
	v_mov_b32_e32 v36, v42
	v_mov_b32_e32 v37, v10
	v_mov_b32_e32 v10, v43
	v_mov_b32_e32 v42, v44
	v_mov_b32_e32 v43, v12
	v_mov_b32_e32 v12, v45
	v_mov_b32_e32 v44, v46
	v_mov_b32_e32 v45, v30
	v_mov_b32_e32 v30, v47
	v_mov_b32_e32 v46, v48
	v_mov_b32_e32 v47, v32
	v_mov_b32_e32 v32, v49
	v_mov_b32_e32 v48, v58
	v_mov_b32_e32 v49, v26
	v_mov_b32_e32 v26, v59
	v_mov_b32_e32 v58, v60
	v_mov_b32_e32 v59, v28
	v_mov_b32_e32 v28, v61
	v_mov_b32_e32 v60, v66
	v_mov_b32_e32 v61, v50
	v_mov_b32_e32 v50, v67
	v_mov_b32_e32 v66, v68
	v_mov_b32_e32 v67, v52
	v_mov_b32_e32 v52, v69
	v_mov_b32_e32 v68, v74
	v_mov_b32_e32 v69, v38
	v_mov_b32_e32 v38, v75
	v_mov_b32_e32 v74, v76
	v_mov_b32_e32 v75, v40
	v_mov_b32_e32 v40, v77
	v_mov_b32_e32 v76, v78
	v_mov_b32_e32 v77, v62
	v_mov_b32_e32 v62, v79
	v_mov_b32_e32 v78, v80
	v_mov_b32_e32 v79, v64
	v_mov_b32_e32 v64, v81
	v_mov_b32_e32 v80, v86
	v_mov_b32_e32 v81, v54
	v_mov_b32_e32 v54, v87
	v_mov_b32_e32 v86, v88
	v_mov_b32_e32 v87, v56
	v_mov_b32_e32 v56, v89
	v_mov_b32_e32 v88, v94
	s_waitcnt lgkmcnt(13)
	v_mov_b32_e32 v89, v82
	v_mov_b32_e32 v82, v95
	v_mov_b32_e32 v94, v96
	v_mov_b32_e32 v95, v84
	v_mov_b32_e32 v84, v97
	v_mov_b32_e32 v96, v102
	s_waitcnt lgkmcnt(12)
	v_mov_b32_e32 v97, v70
	v_mov_b32_e32 v70, v103
	v_mov_b32_e32 v102, v104
	v_mov_b32_e32 v103, v72
	v_mov_b32_e32 v72, v105
	s_waitcnt lgkmcnt(11)
	v_mov_b32_e32 v104, v110
	s_waitcnt lgkmcnt(9)
	v_mov_b32_e32 v105, v98
	v_mov_b32_e32 v98, v111
	v_mov_b32_e32 v110, v112
	v_mov_b32_e32 v111, v100
	v_mov_b32_e32 v100, v113
	v_mov_b32_e32 v112, v114
	s_waitcnt lgkmcnt(8)
	v_mov_b32_e32 v113, v90
	v_mov_b32_e32 v90, v115
	v_mov_b32_e32 v114, v116
	v_mov_b32_e32 v115, v92
	v_mov_b32_e32 v92, v117
	s_waitcnt lgkmcnt(7)
	v_mov_b32_e32 v116, v122
	s_waitcnt lgkmcnt(5)
	v_mov_b32_e32 v117, v118
	v_mov_b32_e32 v118, v123
	v_mov_b32_e32 v122, v124
	v_mov_b32_e32 v123, v120
	v_mov_b32_e32 v120, v125
	v_mov_b32_e32 v124, v126
	s_waitcnt lgkmcnt(4)
	v_mov_b32_e32 v125, v106
	v_mov_b32_e32 v106, v127
	v_mov_b32_e32 v126, v128
	v_mov_b32_e32 v127, v108
	v_mov_b32_e32 v108, v129
	s_waitcnt lgkmcnt(3)
	v_mov_b32_e32 v128, v159
	v_mov_b32_e32 v129, v160
	v_fmac_f32_e32 v182, v186, v158
	v_pk_mul_f32 v[128:129], v[188:189], v[128:129]
	v_pk_fma_f32 v[146:147], v[186:187], v[170:171], v[146:147] op_sel_hi:[0,1,1]
	v_pk_fma_f32 v[20:21], v[186:187], v[20:21], v[142:143] op_sel_hi:[0,1,1]
	v_pk_fma_f32 v[44:45], v[186:187], v[44:45], v[144:145] op_sel_hi:[0,1,1]
	v_pk_fma_f32 v[60:61], v[186:187], v[60:61], v[148:149] op_sel_hi:[0,1,1]
	v_pk_fma_f32 v[76:77], v[186:187], v[76:77], v[150:151] op_sel_hi:[0,1,1]
	v_pk_fma_f32 v[88:89], v[186:187], v[88:89], v[152:153] op_sel_hi:[0,1,1]
	v_pk_fma_f32 v[104:105], v[186:187], v[104:105], v[154:155] op_sel_hi:[0,1,1]
	v_pk_fma_f32 v[116:117], v[186:187], v[116:117], v[156:157] op_sel_hi:[0,1,1]
	s_waitcnt lgkmcnt(2)
	v_pk_mul_f32 v[158:159], v[162:163], v[166:167]
	v_mov_b32_e32 v166, v189
	v_add_f32_e32 v128, v182, v128
	v_pk_fma_f32 v[6:7], v[188:189], v[6:7], v[146:147] op_sel_hi:[0,1,1]
	v_pk_fma_f32 v[14:15], v[188:189], v[14:15], v[20:21] op_sel_hi:[0,1,1]
	v_pk_fma_f32 v[20:21], v[188:189], v[30:31], v[44:45] op_sel_hi:[0,1,1]
	v_pk_fma_f32 v[30:31], v[188:189], v[50:51], v[60:61] op_sel_hi:[0,1,1]
	v_pk_fma_f32 v[44:45], v[188:189], v[62:63], v[76:77] op_sel_hi:[0,1,1]
	v_pk_fma_f32 v[50:51], v[188:189], v[82:83], v[88:89] op_sel_hi:[0,1,1]
	v_pk_fma_f32 v[60:61], v[188:189], v[98:99], v[104:105] op_sel_hi:[0,1,1]
	v_pk_fma_f32 v[62:63], v[188:189], v[118:119], v[116:117] op_sel_hi:[0,1,1]
	v_add_f32_e32 v76, v128, v129
	v_pk_fma_f32 v[6:7], v[166:167], v[22:23], v[6:7] op_sel_hi:[0,1,1]
	v_pk_fma_f32 v[14:15], v[166:167], v[34:35], v[14:15] op_sel_hi:[0,1,1]
	v_pk_fma_f32 v[20:21], v[166:167], v[46:47], v[20:21] op_sel_hi:[0,1,1]
	v_pk_fma_f32 v[22:23], v[166:167], v[66:67], v[30:31] op_sel_hi:[0,1,1]
	v_pk_fma_f32 v[30:31], v[166:167], v[78:79], v[44:45] op_sel_hi:[0,1,1]
	v_pk_fma_f32 v[34:35], v[166:167], v[94:95], v[50:51] op_sel_hi:[0,1,1]
	v_pk_fma_f32 v[44:45], v[166:167], v[110:111], v[60:61] op_sel_hi:[0,1,1]
	v_pk_fma_f32 v[46:47], v[166:167], v[122:123], v[62:63] op_sel_hi:[0,1,1]
	s_waitcnt lgkmcnt(1)
; DI void phase_prologue(const Params& p, int bid, int nblk, char* smem) {
;     ...
;       for (int k0 = kq * 256; k0 < kq * 256 + 256; k0 += 8) {
;         float wv[8];
; #pragma unroll
;         for (int kk = 0; kk < 8; ++kk) wv[kk] = wa[(size_t)(k0 + kk) * 6144];
; #pragma unroll
;         for (int kk = 0; kk < 8; ++kk)
; #pragma unroll
;           for (int j = 0; j < 17; ++j) acc[j] += scs[j * 1024 + k0 + kk] * wv[kk];
;       }
	v_pk_mul_f32 v[160:161], v[164:165], v[168:169]
	v_mov_b32_e32 v168, v163
	v_add_f32_e32 v50, v76, v158
	v_pk_fma_f32 v[6:7], v[162:163], v[8:9], v[6:7] op_sel_hi:[0,1,1]
	v_pk_fma_f32 v[8:9], v[162:163], v[16:17], v[14:15] op_sel_hi:[0,1,1]
	v_pk_fma_f32 v[14:15], v[162:163], v[32:33], v[20:21] op_sel_hi:[0,1,1]
	v_pk_fma_f32 v[16:17], v[162:163], v[52:53], v[22:23] op_sel_hi:[0,1,1]
	v_pk_fma_f32 v[20:21], v[162:163], v[64:65], v[30:31] op_sel_hi:[0,1,1]
	v_pk_fma_f32 v[22:23], v[162:163], v[84:85], v[34:35] op_sel_hi:[0,1,1]
	v_pk_fma_f32 v[30:31], v[162:163], v[100:101], v[44:45] op_sel_hi:[0,1,1]
	v_pk_fma_f32 v[32:33], v[162:163], v[120:121], v[46:47] op_sel_hi:[0,1,1]
	v_add_f32_e32 v34, v50, v159
	v_pk_fma_f32 v[6:7], v[168:169], v[24:25], v[6:7] op_sel_hi:[0,1,1]
	v_pk_fma_f32 v[8:9], v[168:169], v[36:37], v[8:9] op_sel_hi:[0,1,1]
	v_pk_fma_f32 v[14:15], v[168:169], v[48:49], v[14:15] op_sel_hi:[0,1,1]
	v_pk_fma_f32 v[16:17], v[168:169], v[68:69], v[16:17] op_sel_hi:[0,1,1]
	v_pk_fma_f32 v[20:21], v[168:169], v[80:81], v[20:21] op_sel_hi:[0,1,1]
	v_pk_fma_f32 v[22:23], v[168:169], v[96:97], v[22:23] op_sel_hi:[0,1,1]
	v_pk_fma_f32 v[24:25], v[168:169], v[112:113], v[30:31] op_sel_hi:[0,1,1]
	v_pk_fma_f32 v[30:31], v[168:169], v[124:125], v[32:33] op_sel_hi:[0,1,1]
	v_mov_b32_e32 v170, v165
	v_add_f32_e32 v32, v34, v160
	v_pk_fma_f32 v[2:3], v[164:165], v[2:3], v[6:7] op_sel_hi:[0,1,1]
	v_pk_fma_f32 v[6:7], v[164:165], v[10:11], v[8:9] op_sel_hi:[0,1,1]
	v_pk_fma_f32 v[8:9], v[164:165], v[26:27], v[14:15] op_sel_hi:[0,1,1]
	v_pk_fma_f32 v[10:11], v[164:165], v[38:39], v[16:17] op_sel_hi:[0,1,1]
	v_pk_fma_f32 v[14:15], v[164:165], v[54:55], v[20:21] op_sel_hi:[0,1,1]
	v_pk_fma_f32 v[16:17], v[164:165], v[70:71], v[22:23] op_sel_hi:[0,1,1]
	v_pk_fma_f32 v[20:21], v[164:165], v[90:91], v[24:25] op_sel_hi:[0,1,1]
	v_pk_fma_f32 v[22:23], v[164:165], v[106:107], v[30:31] op_sel_hi:[0,1,1]
	v_cmp_ge_i32_e32 vcc, v181, v133
	v_add_f32_e32 v182, v32, v161
	v_pk_fma_f32 v[2:3], v[170:171], v[18:19], v[2:3] op_sel_hi:[0,1,1]
	v_pk_fma_f32 v[6:7], v[170:171], v[42:43], v[6:7] op_sel_hi:[0,1,1]
	v_pk_fma_f32 v[8:9], v[170:171], v[58:59], v[8:9] op_sel_hi:[0,1,1]
	v_pk_fma_f32 v[10:11], v[170:171], v[74:75], v[10:11] op_sel_hi:[0,1,1]
	v_pk_fma_f32 v[14:15], v[170:171], v[86:87], v[14:15] op_sel_hi:[0,1,1]
	v_pk_fma_f32 v[16:17], v[170:171], v[102:103], v[16:17] op_sel_hi:[0,1,1]
	v_pk_fma_f32 v[18:19], v[170:171], v[114:115], v[20:21] op_sel_hi:[0,1,1]
	v_pk_fma_f32 v[20:21], v[170:171], v[126:127], v[22:23] op_sel_hi:[0,1,1]
	v_add_u32_e32 v180, 32, v180
	v_lshl_add_u64 v[140:141], v[140:141], 0, s[24:25]
	s_or_b64 s[18:19], vcc, s[18:19]
	v_pk_fma_f32 v[146:147], v[134:135], v[4:5], v[2:3] op_sel_hi:[0,1,1]
	v_pk_fma_f32 v[142:143], v[134:135], v[12:13], v[6:7] op_sel_hi:[0,1,1]
	v_pk_fma_f32 v[144:145], v[134:135], v[28:29], v[8:9] op_sel_hi:[0,1,1]
	v_pk_fma_f32 v[148:149], v[134:135], v[40:41], v[10:11] op_sel_hi:[0,1,1]
	v_pk_fma_f32 v[150:151], v[134:135], v[56:57], v[14:15] op_sel_hi:[0,1,1]
	v_pk_fma_f32 v[152:153], v[134:135], v[72:73], v[16:17] op_sel_hi:[0,1,1]
	v_pk_fma_f32 v[154:155], v[134:135], v[92:93], v[18:19] op_sel_hi:[0,1,1]
	v_pk_fma_f32 v[156:157], v[134:135], v[108:109], v[20:21] op_sel_hi:[0,1,1]
	s_waitcnt lgkmcnt(0)
	v_fmac_f32_e32 v182, v134, v183
	s_waitcnt vmcnt(16)
	v_mov_b32_e32 v134, v244
	v_mov_b32_e32 v186, v245
	v_mov_b32_e32 v188, v246
	v_mov_b32_e32 v189, v247
	v_mov_b32_e32 v162, v248
	v_mov_b32_e32 v163, v249
	v_mov_b32_e32 v164, v250
	v_mov_b32_e32 v165, v251
	s_nop 0
	ds_read_b128 v[22:25], v180
	ds_read_b128 v[18:21], v180 offset:16
	ds_read_b128 v[6:9], v180 offset:4096
	ds_read_b128 v[2:5], v180 offset:4112
	ds_read_b128 v[34:37], v180 offset:8192
	ds_read_b128 v[42:45], v180 offset:8208
	ds_read_b128 v[14:17], v180 offset:12288
	ds_read_b128 v[10:13], v180 offset:12304
	ds_read_b128 v[46:49], v180 offset:16384
	ds_read_b128 v[58:61], v180 offset:16400
	ds_read_b128 v[30:33], v180 offset:20480
	ds_read_b128 v[26:29], v180 offset:20496
	ds_read_b128 v[66:69], v180 offset:24576
	ds_read_b128 v[74:77], v180 offset:24592
	ds_read_b128 v[50:53], v180 offset:28672
	ds_read_b128 v[38:41], v180 offset:28688
	ds_read_b128 v[78:81], v180 offset:32768
	ds_read_b128 v[86:89], v180 offset:32784
	ds_read_b128 v[62:65], v180 offset:36864
	ds_read_b128 v[54:57], v180 offset:36880
	ds_read_b128 v[94:97], v180 offset:40960
	ds_read_b128 v[102:105], v180 offset:40976
	ds_read_b128 v[82:85], v180 offset:45056
	ds_read_b128 v[70:73], v180 offset:45072
	ds_read_b128 v[110:113], v180 offset:49152
	ds_read_b128 v[114:117], v180 offset:49168
	ds_read_b128 v[98:101], v180 offset:53248
	ds_read_b128 v[90:93], v180 offset:53264
	ds_read_b128 v[122:125], v180 offset:57344
	ds_read_b128 v[126:129], v180 offset:57360
	ds_read_b128 v[118:121], v180 offset:61440
	ds_read_b128 v[106:109], v180 offset:61456
	v_add_u32_e32 v183, 0x10000, v180
	s_nop 0
	v_add_u32_e32 v184, 0x1000c, v180
	s_nop 0
	v_add_u32_e32 v185, 0x10014, v180
	s_nop 0
	v_add_u32_e32 v187, 0x1001c, v180
	s_nop 0
	v_add_u32_e32 v181, 8, v181
	v_add_u32_e32 v242, 16, v181
	v_mov_b32_e32 v216, 0x90000
	v_cmp_lt_i32_e32 vcc, v242, v133
	s_nop 1
	v_cndmask_b32_e32 v216, 0, v216, vcc
	v_mov_b32_e32 v217, 0
	v_lshl_add_u64 v[240:241], v[140:141], 0, v[216:217]
	global_load_dword v208, v[240:241], off
	v_lshl_add_u64 v[226:227], v[240:241], 0, s[56:57]
	global_load_dword v215, v[226:227], off
	v_lshl_add_u64 v[228:229], v[226:227], 0, s[56:57]
	global_load_dword v214, v[228:229], off
	v_lshl_add_u64 v[230:231], v[228:229], 0, s[56:57]
	global_load_dword v213, v[230:231], off
	v_lshl_add_u64 v[232:233], v[230:231], 0, s[56:57]
	global_load_dword v212, v[232:233], off
	v_lshl_add_u64 v[234:235], v[232:233], 0, s[56:57]
	global_load_dword v211, v[234:235], off
	v_lshl_add_u64 v[236:237], v[234:235], 0, s[56:57]
	global_load_dword v210, v[236:237], off
	v_lshl_add_u64 v[238:239], v[236:237], 0, s[56:57]
	global_load_dword v209, v[238:239], off
	s_nop 0
	s_nop 0
	s_nop 0
	ds_read_b96 v[158:160], v183
	ds_read2_b32 v[166:167], v184 offset1:1
	ds_read2_b32 v[168:169], v185 offset1:1
	ds_read_b32 v183, v187
	s_waitcnt lgkmcnt(14)
; DI void phase_prologue(const Params& p, int bid, int nblk, char* smem) {
;     ...
;       for (int k0 = kq * 256; k0 < kq * 256 + 256; k0 += 8) {
;         float wv[8];
; #pragma unroll
;         for (int kk = 0; kk < 8; ++kk) wv[kk] = wa[(size_t)(k0 + kk) * 6144];
; #pragma unroll
;         for (int kk = 0; kk < 8; ++kk)
; #pragma unroll
;           for (int j = 0; j < 17; ++j) acc[j] += scs[j * 1024 + k0 + kk] * wv[kk];
;       }
	v_mov_b32_e32 v170, v22
	v_mov_b32_e32 v171, v6
	v_mov_b32_e32 v6, v23
	v_mov_b32_e32 v22, v24
	v_mov_b32_e32 v23, v8
	v_mov_b32_e32 v8, v25
	v_mov_b32_e32 v24, v18
	v_mov_b32_e32 v25, v2
	v_mov_b32_e32 v2, v19
	v_mov_b32_e32 v18, v20
	v_mov_b32_e32 v19, v4
	v_mov_b32_e32 v4, v21
	v_mov_b32_e32 v20, v34
	v_mov_b32_e32 v21, v14
	v_mov_b32_e32 v14, v35
	v_mov_b32_e32 v34, v36
	v_mov_b32_e32 v35, v16
	v_mov_b32_e32 v16, v37
	v_mov_b32_e32 v36, v42
	v_mov_b32_e32 v37, v10
	v_mov_b32_e32 v10, v43
	v_mov_b32_e32 v42, v44
	v_mov_b32_e32 v43, v12
	v_mov_b32_e32 v12, v45
	v_mov_b32_e32 v44, v46
	v_mov_b32_e32 v45, v30
	v_mov_b32_e32 v30, v47
	v_mov_b32_e32 v46, v48
	v_mov_b32_e32 v47, v32
	v_mov_b32_e32 v32, v49
	v_mov_b32_e32 v48, v58
	v_mov_b32_e32 v49, v26
	v_mov_b32_e32 v26, v59
	v_mov_b32_e32 v58, v60
	v_mov_b32_e32 v59, v28
	v_mov_b32_e32 v28, v61
	v_mov_b32_e32 v60, v66
	v_mov_b32_e32 v61, v50
	v_mov_b32_e32 v50, v67
	v_mov_b32_e32 v66, v68
	v_mov_b32_e32 v67, v52
	v_mov_b32_e32 v52, v69
	v_mov_b32_e32 v68, v74
	v_mov_b32_e32 v69, v38
	v_mov_b32_e32 v38, v75
	v_mov_b32_e32 v74, v76
	v_mov_b32_e32 v75, v40
	v_mov_b32_e32 v40, v77
	v_mov_b32_e32 v76, v78
	v_mov_b32_e32 v77, v62
	v_mov_b32_e32 v62, v79
	v_mov_b32_e32 v78, v80
	v_mov_b32_e32 v79, v64
	v_mov_b32_e32 v64, v81
	v_mov_b32_e32 v80, v86
	v_mov_b32_e32 v81, v54
	v_mov_b32_e32 v54, v87
	v_mov_b32_e32 v86, v88
	v_mov_b32_e32 v87, v56
	v_mov_b32_e32 v56, v89
	v_mov_b32_e32 v88, v94
	s_waitcnt lgkmcnt(13)
	v_mov_b32_e32 v89, v82
	v_mov_b32_e32 v82, v95
	v_mov_b32_e32 v94, v96
	v_mov_b32_e32 v95, v84
	v_mov_b32_e32 v84, v97
	v_mov_b32_e32 v96, v102
	s_waitcnt lgkmcnt(12)
	v_mov_b32_e32 v97, v70
	v_mov_b32_e32 v70, v103
	v_mov_b32_e32 v102, v104
	v_mov_b32_e32 v103, v72
	v_mov_b32_e32 v72, v105
	s_waitcnt lgkmcnt(11)
	v_mov_b32_e32 v104, v110
	s_waitcnt lgkmcnt(9)
	v_mov_b32_e32 v105, v98
	v_mov_b32_e32 v98, v111
	v_mov_b32_e32 v110, v112
	v_mov_b32_e32 v111, v100
	v_mov_b32_e32 v100, v113
	v_mov_b32_e32 v112, v114
	s_waitcnt lgkmcnt(8)
	v_mov_b32_e32 v113, v90
	v_mov_b32_e32 v90, v115
	v_mov_b32_e32 v114, v116
	v_mov_b32_e32 v115, v92
	v_mov_b32_e32 v92, v117
	s_waitcnt lgkmcnt(7)
	v_mov_b32_e32 v116, v122
	s_waitcnt lgkmcnt(5)
	v_mov_b32_e32 v117, v118
	v_mov_b32_e32 v118, v123
	v_mov_b32_e32 v122, v124
	v_mov_b32_e32 v123, v120
	v_mov_b32_e32 v120, v125
	v_mov_b32_e32 v124, v126
	s_waitcnt lgkmcnt(4)
	v_mov_b32_e32 v125, v106
	v_mov_b32_e32 v106, v127
	v_mov_b32_e32 v126, v128
	v_mov_b32_e32 v127, v108
	v_mov_b32_e32 v108, v129
	s_waitcnt lgkmcnt(3)
	v_mov_b32_e32 v128, v159
	v_mov_b32_e32 v129, v160
	v_fmac_f32_e32 v182, v186, v158
	v_pk_mul_f32 v[128:129], v[188:189], v[128:129]
	v_pk_fma_f32 v[146:147], v[186:187], v[170:171], v[146:147] op_sel_hi:[0,1,1]
	v_pk_fma_f32 v[20:21], v[186:187], v[20:21], v[142:143] op_sel_hi:[0,1,1]
	v_pk_fma_f32 v[44:45], v[186:187], v[44:45], v[144:145] op_sel_hi:[0,1,1]
	v_pk_fma_f32 v[60:61], v[186:187], v[60:61], v[148:149] op_sel_hi:[0,1,1]
	v_pk_fma_f32 v[76:77], v[186:187], v[76:77], v[150:151] op_sel_hi:[0,1,1]
	v_pk_fma_f32 v[88:89], v[186:187], v[88:89], v[152:153] op_sel_hi:[0,1,1]
	v_pk_fma_f32 v[104:105], v[186:187], v[104:105], v[154:155] op_sel_hi:[0,1,1]
	v_pk_fma_f32 v[116:117], v[186:187], v[116:117], v[156:157] op_sel_hi:[0,1,1]
	s_waitcnt lgkmcnt(2)
	v_pk_mul_f32 v[158:159], v[162:163], v[166:167]
	v_mov_b32_e32 v166, v189
	v_add_f32_e32 v128, v182, v128
	v_pk_fma_f32 v[6:7], v[188:189], v[6:7], v[146:147] op_sel_hi:[0,1,1]
	v_pk_fma_f32 v[14:15], v[188:189], v[14:15], v[20:21] op_sel_hi:[0,1,1]
	v_pk_fma_f32 v[20:21], v[188:189], v[30:31], v[44:45] op_sel_hi:[0,1,1]
	v_pk_fma_f32 v[30:31], v[188:189], v[50:51], v[60:61] op_sel_hi:[0,1,1]
	v_pk_fma_f32 v[44:45], v[188:189], v[62:63], v[76:77] op_sel_hi:[0,1,1]
	v_pk_fma_f32 v[50:51], v[188:189], v[82:83], v[88:89] op_sel_hi:[0,1,1]
	v_pk_fma_f32 v[60:61], v[188:189], v[98:99], v[104:105] op_sel_hi:[0,1,1]
	v_pk_fma_f32 v[62:63], v[188:189], v[118:119], v[116:117] op_sel_hi:[0,1,1]
	v_add_f32_e32 v76, v128, v129
	v_pk_fma_f32 v[6:7], v[166:167], v[22:23], v[6:7] op_sel_hi:[0,1,1]
	v_pk_fma_f32 v[14:15], v[166:167], v[34:35], v[14:15] op_sel_hi:[0,1,1]
	v_pk_fma_f32 v[20:21], v[166:167], v[46:47], v[20:21] op_sel_hi:[0,1,1]
	v_pk_fma_f32 v[22:23], v[166:167], v[66:67], v[30:31] op_sel_hi:[0,1,1]
	v_pk_fma_f32 v[30:31], v[166:167], v[78:79], v[44:45] op_sel_hi:[0,1,1]
	v_pk_fma_f32 v[34:35], v[166:167], v[94:95], v[50:51] op_sel_hi:[0,1,1]
	v_pk_fma_f32 v[44:45], v[166:167], v[110:111], v[60:61] op_sel_hi:[0,1,1]
	v_pk_fma_f32 v[46:47], v[166:167], v[122:123], v[62:63] op_sel_hi:[0,1,1]
	s_waitcnt lgkmcnt(1)
; DI void phase_prologue(const Params& p, int bid, int nblk, char* smem) {
;     ...
;       for (int k0 = kq * 256; k0 < kq * 256 + 256; k0 += 8) {
;         float wv[8];
; #pragma unroll
;         for (int kk = 0; kk < 8; ++kk) wv[kk] = wa[(size_t)(k0 + kk) * 6144];
; #pragma unroll
;         for (int kk = 0; kk < 8; ++kk)
; #pragma unroll
;           for (int j = 0; j < 17; ++j) acc[j] += scs[j * 1024 + k0 + kk] * wv[kk];
;       }
;       __syncthreads();
; #pragma unroll
;       for (int j = 0; j < 17; ++j) scs[(kq * 17 + j) * 64 + col] = acc[j];
;       __syncthreads();
;       for (int e = tid; e < 17 * 64; e += NTHR) {
;         const int j = e >> 6, cc = e & 63;
;         float s = p.in[I_BADA][l * 6144 + col0 + cc];
; #pragma unroll
;         for (int q = 0; q < 4; ++q) s += scs[(q * 17 + j) * 64 + cc];
;         WSP(float, OFF_MOD)[(size_t)(l * 17 + j) * 6144 + col0 + cc] = s;
	v_pk_mul_f32 v[160:161], v[164:165], v[168:169]
	v_mov_b32_e32 v168, v163
	v_add_f32_e32 v50, v76, v158
	v_pk_fma_f32 v[6:7], v[162:163], v[8:9], v[6:7] op_sel_hi:[0,1,1]
	v_pk_fma_f32 v[8:9], v[162:163], v[16:17], v[14:15] op_sel_hi:[0,1,1]
	v_pk_fma_f32 v[14:15], v[162:163], v[32:33], v[20:21] op_sel_hi:[0,1,1]
	v_pk_fma_f32 v[16:17], v[162:163], v[52:53], v[22:23] op_sel_hi:[0,1,1]
	v_pk_fma_f32 v[20:21], v[162:163], v[64:65], v[30:31] op_sel_hi:[0,1,1]
	v_pk_fma_f32 v[22:23], v[162:163], v[84:85], v[34:35] op_sel_hi:[0,1,1]
	v_pk_fma_f32 v[30:31], v[162:163], v[100:101], v[44:45] op_sel_hi:[0,1,1]
	v_pk_fma_f32 v[32:33], v[162:163], v[120:121], v[46:47] op_sel_hi:[0,1,1]
	v_add_f32_e32 v34, v50, v159
	v_pk_fma_f32 v[6:7], v[168:169], v[24:25], v[6:7] op_sel_hi:[0,1,1]
	v_pk_fma_f32 v[8:9], v[168:169], v[36:37], v[8:9] op_sel_hi:[0,1,1]
	v_pk_fma_f32 v[14:15], v[168:169], v[48:49], v[14:15] op_sel_hi:[0,1,1]
	v_pk_fma_f32 v[16:17], v[168:169], v[68:69], v[16:17] op_sel_hi:[0,1,1]
	v_pk_fma_f32 v[20:21], v[168:169], v[80:81], v[20:21] op_sel_hi:[0,1,1]
	v_pk_fma_f32 v[22:23], v[168:169], v[96:97], v[22:23] op_sel_hi:[0,1,1]
	v_pk_fma_f32 v[24:25], v[168:169], v[112:113], v[30:31] op_sel_hi:[0,1,1]
	v_pk_fma_f32 v[30:31], v[168:169], v[124:125], v[32:33] op_sel_hi:[0,1,1]
	v_mov_b32_e32 v170, v165
	v_add_f32_e32 v32, v34, v160
	v_pk_fma_f32 v[2:3], v[164:165], v[2:3], v[6:7] op_sel_hi:[0,1,1]
	v_pk_fma_f32 v[6:7], v[164:165], v[10:11], v[8:9] op_sel_hi:[0,1,1]
	v_pk_fma_f32 v[8:9], v[164:165], v[26:27], v[14:15] op_sel_hi:[0,1,1]
	v_pk_fma_f32 v[10:11], v[164:165], v[38:39], v[16:17] op_sel_hi:[0,1,1]
	v_pk_fma_f32 v[14:15], v[164:165], v[54:55], v[20:21] op_sel_hi:[0,1,1]
	v_pk_fma_f32 v[16:17], v[164:165], v[70:71], v[22:23] op_sel_hi:[0,1,1]
	v_pk_fma_f32 v[20:21], v[164:165], v[90:91], v[24:25] op_sel_hi:[0,1,1]
	v_pk_fma_f32 v[22:23], v[164:165], v[106:107], v[30:31] op_sel_hi:[0,1,1]
	v_cmp_ge_i32_e32 vcc, v181, v133
	v_add_f32_e32 v182, v32, v161
	v_pk_fma_f32 v[2:3], v[170:171], v[18:19], v[2:3] op_sel_hi:[0,1,1]
	v_pk_fma_f32 v[6:7], v[170:171], v[42:43], v[6:7] op_sel_hi:[0,1,1]
	v_pk_fma_f32 v[8:9], v[170:171], v[58:59], v[8:9] op_sel_hi:[0,1,1]
	v_pk_fma_f32 v[10:11], v[170:171], v[74:75], v[10:11] op_sel_hi:[0,1,1]
	v_pk_fma_f32 v[14:15], v[170:171], v[86:87], v[14:15] op_sel_hi:[0,1,1]
	v_pk_fma_f32 v[16:17], v[170:171], v[102:103], v[16:17] op_sel_hi:[0,1,1]
	v_pk_fma_f32 v[18:19], v[170:171], v[114:115], v[20:21] op_sel_hi:[0,1,1]
	v_pk_fma_f32 v[20:21], v[170:171], v[126:127], v[22:23] op_sel_hi:[0,1,1]
	v_add_u32_e32 v180, 32, v180
	v_lshl_add_u64 v[140:141], v[140:141], 0, s[24:25]
	s_or_b64 s[18:19], vcc, s[18:19]
	v_pk_fma_f32 v[146:147], v[134:135], v[4:5], v[2:3] op_sel_hi:[0,1,1]
	v_pk_fma_f32 v[142:143], v[134:135], v[12:13], v[6:7] op_sel_hi:[0,1,1]
	v_pk_fma_f32 v[144:145], v[134:135], v[28:29], v[8:9] op_sel_hi:[0,1,1]
	v_pk_fma_f32 v[148:149], v[134:135], v[40:41], v[10:11] op_sel_hi:[0,1,1]
	v_pk_fma_f32 v[150:151], v[134:135], v[56:57], v[14:15] op_sel_hi:[0,1,1]
	v_pk_fma_f32 v[152:153], v[134:135], v[72:73], v[16:17] op_sel_hi:[0,1,1]
	v_pk_fma_f32 v[154:155], v[134:135], v[92:93], v[18:19] op_sel_hi:[0,1,1]
	v_pk_fma_f32 v[156:157], v[134:135], v[108:109], v[20:21] op_sel_hi:[0,1,1]
	s_waitcnt lgkmcnt(0)
	v_fmac_f32_e32 v182, v134, v183
	s_andn2_b64 exec, exec, s[18:19]
	s_cbranch_execnz .LBB0_23
	s_or_b64 exec, exec, s[18:19]
	s_waitcnt vmcnt(0)
	s_barrier
	ds_write2st64_b32 v178, v146, v147 offset1:1
	ds_write2st64_b32 v178, v142, v143 offset0:2 offset1:3
	ds_write2st64_b32 v178, v144, v145 offset0:4 offset1:5
	ds_write2st64_b32 v178, v148, v149 offset0:6 offset1:7
	ds_write2st64_b32 v178, v150, v151 offset0:8 offset1:9
	ds_write2st64_b32 v178, v152, v153 offset0:10 offset1:11
	ds_write2st64_b32 v178, v154, v155 offset0:12 offset1:13
	ds_write2st64_b32 v178, v156, v157 offset0:14 offset1:15
	ds_write_b32 v178, v182 offset:4096
	s_waitcnt lgkmcnt(0)
	s_barrier
	s_and_saveexec_b64 s[18:19], s[4:5]
	s_cbranch_execz .LBB0_7
	s_load_dwordx16 s[56:71], s[0:1], 0x0
	s_mul_i32 s21, s20, 0x1800
	s_add_i32 s21, s21, s16
	v_or_b32_e32 v2, s21, v132
	v_ashrrev_i32_e32 v3, 31, v2
	s_mul_i32 s20, s20, 17
	s_waitcnt lgkmcnt(0)
	v_lshl_add_u64 v[2:3], v[2:3], 2, s[66:67]
	v_lshl_add_u64 v[4:5], s[16:17], 2, v[136:137]
	s_mov_b64 s[16:17], 0
	v_mov_b32_e32 v6, v130
